# rec_pass1: next item's operand lines touched (scalar-addressed dummy loads) while the current item computes
# baseline (speedup 1.0000x reference)
.LBB0_190:
	s_cmpk_gt_i32 s20, 0xff
	s_mov_b64 s[2:3], -1
	s_cbranch_scc0 .LBB0_292
	s_lshl_b32 s6, s20, 1
	s_cmpk_gt_u32 s20, 0x2ff
	s_cbranch_scc0 .LBB0_231
	v_mov_b32_e32 v0, v206
	s_add_i32 s2, s6, 0xfffffa00
	v_ashrrev_i32_e32 v0, 8, v0
	v_mov_b32_e32 v106, v206
	v_mov_b32_e32 v111, v206
	v_add_u32_e32 v102, s2, v0
	v_mov_b32_e32 v1, v206
	v_bfe_u32 v2, v111, 6, 2
	s_movk_i32 s2, 0x100
	v_ashrrev_i32_e32 v0, 9, v102
	v_xor_b32_e32 v3, 3, v2
	v_cmp_gt_u32_e32 vcc, s2, v1
	v_ashrrev_i32_e32 v1, 31, v0
	v_and_b32_e32 v107, 15, v111
	v_cndmask_b32_e32 v108, v3, v2, vcc
	v_lshlrev_b64 v[100:101], 13, v[0:1]
	v_lshlrev_b32_e32 v0, 6, v102
	s_movk_i32 s2, 0x1fc0
	v_lshlrev_b32_e32 v113, 4, v108
	v_and_or_b32 v12, v0, s2, v100
	v_or_b32_e32 v110, v113, v107
	v_or_b32_e32 v100, v12, v110
	v_mov_b64_e32 v[0:1], s[68:69]
	v_bfe_u32 v8, v102, 7, 2
	v_mad_u64_u32 v[0:1], s[2:3], v100, s13, v[0:1]
	v_bfe_u32 v112, v111, 4, 2
	v_mad_i32_i24 v1, v101, s13, v1
	v_lshlrev_b32_e32 v176, 6, v8
	v_lshl_add_u64 v[0:1], v[0:1], 0, v[176:177]
	v_lshlrev_b32_e32 v2, 4, v112
	v_mov_b32_e32 v3, v177
	v_lshl_add_u64 v[0:1], v[0:1], 0, v[2:3]
	s_mov_b32 s2, 0x3e80000
	v_add_co_u32_e32 v0, vcc, s2, v0
	v_mov_b32_e32 v115, v206
	s_nop 0
	v_addc_co_u32_e32 v1, vcc, 0, v1, vcc
	global_load_dwordx4 v[0:3], v[0:1], off offset:3584
	v_lshlrev_b32_e32 v104, 7, v8
	v_bfe_u32 v116, v115, 2, 6
	v_lshlrev_b32_e32 v4, 4, v115
	v_and_b32_e32 v117, 48, v4
	v_or_b32_e32 v6, v12, v116
	v_mov_b64_e32 v[4:5], s[76:77]
	v_bfe_u32 v103, v115, 5, 3
	v_mad_u64_u32 v[6:7], s[2:3], v6, s13, v[4:5]
	v_mad_i32_i24 v7, v101, s13, v7
	v_mov_b32_e32 v105, v177
	v_lshlrev_b32_e32 v114, 3, v103
	v_lshlrev_b32_e32 v109, 5, v8
	v_lshl_add_u64 v[6:7], v[6:7], 0, v[104:105]
	v_lshlrev_b32_e32 v8, 1, v117
	v_mov_b32_e32 v9, v177
	v_or_b32_e32 v167, 1, v114
	v_lshl_add_u64 v[6:7], v[6:7], 0, v[8:9]
	s_mov_b64 s[2:3], 0x1000
	v_or_b32_e32 v8, v114, v12
	v_or_b32_e32 v12, v12, v167
	v_mov_b32_e32 v13, v101
	v_lshl_add_u64 v[158:159], v[6:7], 0, s[2:3]
	v_lshlrev_b64 v[14:15], 6, v[12:13]
	v_mad_u64_u32 v[12:13], s[2:3], v12, s13, v[4:5]
	v_and_b32_e32 v166, 31, v115
	v_mov_b32_e32 v9, v101
	v_readlane_b32 s4, v254, 15
	v_mad_i32_i24 v13, v101, s13, v13
	v_lshlrev_b64 v[10:11], 6, v[8:9]
	v_readlane_b32 s5, v254, 16
	v_lshlrev_b32_e32 v40, 1, v166
	v_mov_b32_e32 v41, v177
	v_lshl_add_u64 v[12:13], v[12:13], 0, v[176:177]
	v_lshl_add_u64 v[154:155], s[4:5], 0, v[10:11]
	v_lshl_add_u64 v[14:15], s[4:5], 0, v[14:15]
	v_lshl_add_u64 v[42:43], v[12:13], 0, v[40:41]
	v_or_b32_e32 v12, 2, v8
	v_mov_b32_e32 v13, v101
	global_load_dwordx4 v[118:121], v[154:155], off offset:32
	global_load_dwordx4 v[122:125], v[154:155], off offset:16
	global_load_dwordx4 v[126:129], v[14:15], off offset:48
	global_load_dwordx4 v[130:133], v[14:15], off offset:32
	global_load_dwordx4 v[134:137], v[14:15], off offset:16
	global_load_dwordx4 v[138:141], v[14:15], off
	v_lshlrev_b64 v[14:15], 6, v[12:13]
	v_mad_u64_u32 v[12:13], s[2:3], v12, s13, v[4:5]
	v_mad_i32_i24 v13, v101, s13, v13
	v_lshl_add_u64 v[12:13], v[12:13], 0, v[176:177]
	v_lshl_add_u64 v[58:59], v[12:13], 0, v[40:41]
	v_or_b32_e32 v12, 3, v8
	v_mov_b32_e32 v13, v101
	v_lshl_add_u64 v[56:57], s[4:5], 0, v[14:15]
	v_lshlrev_b64 v[14:15], 6, v[12:13]
	v_mad_u64_u32 v[12:13], s[2:3], v12, s13, v[4:5]
	v_mad_i32_i24 v13, v101, s13, v13
	v_lshl_add_u64 v[12:13], v[12:13], 0, v[176:177]
	v_lshl_add_u64 v[14:15], s[4:5], 0, v[14:15]
	v_lshl_add_u64 v[84:85], v[12:13], 0, v[40:41]
	v_or_b32_e32 v12, 4, v8
	v_mov_b32_e32 v13, v101
	global_load_dwordx4 v[88:91], v[56:57], off offset:32
	global_load_dwordx4 v[92:95], v[56:57], off offset:16
	global_load_dwordx4 v[68:71], v[14:15], off offset:48
	global_load_dwordx4 v[72:75], v[14:15], off offset:32
	global_load_dwordx4 v[76:79], v[14:15], off offset:16
	global_load_dwordx4 v[80:83], v[14:15], off
	v_lshlrev_b64 v[14:15], 6, v[12:13]
	v_mad_u64_u32 v[12:13], s[2:3], v12, s13, v[4:5]
	v_mad_i32_i24 v13, v101, s13, v13
	v_lshl_add_u64 v[12:13], v[12:13], 0, v[176:177]
	v_lshl_add_u64 v[156:157], v[12:13], 0, v[40:41]
	v_or_b32_e32 v12, 5, v8
	v_mov_b32_e32 v13, v101
	v_lshl_add_u64 v[86:87], s[4:5], 0, v[14:15]
	v_lshlrev_b64 v[14:15], 6, v[12:13]
	v_mad_u64_u32 v[12:13], s[2:3], v12, s13, v[4:5]
	v_mad_i32_i24 v13, v101, s13, v13
	v_lshl_add_u64 v[12:13], v[12:13], 0, v[176:177]
	v_lshl_add_u64 v[14:15], s[4:5], 0, v[14:15]
	v_lshl_add_u64 v[160:161], v[12:13], 0, v[40:41]
	v_or_b32_e32 v12, 6, v8
	v_mov_b32_e32 v13, v101
	v_mad_u64_u32 v[10:11], s[2:3], v8, s13, v[4:5]
	global_load_dwordx4 v[60:63], v[86:87], off offset:32
	global_load_dwordx4 v[64:67], v[86:87], off offset:16
	global_load_dwordx4 v[36:39], v[14:15], off offset:48
	global_load_dwordx4 v[44:47], v[14:15], off offset:32
	global_load_dwordx4 v[48:51], v[14:15], off offset:16
	global_load_dwordx4 v[52:55], v[14:15], off
	v_lshlrev_b64 v[14:15], 6, v[12:13]
	v_mad_u64_u32 v[12:13], s[2:3], v12, s13, v[4:5]
	v_or_b32_e32 v8, 7, v8
	v_mad_i32_i24 v13, v101, s13, v13
	v_mad_u64_u32 v[4:5], s[2:3], v8, s13, v[4:5]
	v_mad_i32_i24 v11, v101, s13, v11
	v_lshl_add_u64 v[12:13], v[12:13], 0, v[176:177]
	v_mad_i32_i24 v5, v101, s13, v5
	s_movk_i32 s2, 0x1000
	v_lshl_add_u64 v[10:11], v[10:11], 0, v[176:177]
	v_lshl_add_u64 v[164:165], v[12:13], 0, v[40:41]
	v_lshlrev_b64 v[12:13], 6, v[8:9]
	v_lshl_add_u64 v[4:5], v[4:5], 0, v[176:177]
	v_add_co_u32_e32 v6, vcc, s2, v6
	v_lshl_add_u64 v[10:11], v[10:11], 0, v[40:41]
	v_lshl_add_u64 v[162:163], s[4:5], 0, v[14:15]
	v_lshl_add_u64 v[24:25], s[4:5], 0, v[12:13]
	v_lshl_add_u64 v[4:5], v[4:5], 0, v[40:41]
	v_addc_co_u32_e32 v7, vcc, 0, v7, vcc
	global_load_dwordx4 v[28:31], v[162:163], off offset:32
	global_load_dwordx4 v[32:35], v[162:163], off offset:16
	global_load_dwordx4 v[12:15], v[24:25], off offset:48
	global_load_dwordx4 v[16:19], v[24:25], off offset:32
	global_load_dwordx4 v[20:23], v[24:25], off offset:16
	s_nop 0
	global_load_dwordx4 v[24:27], v[24:25], off
	s_nop 0
	global_load_dwordx4 v[142:145], v[154:155], off offset:48
	global_load_ushort v168, v[10:11], off offset:3840
	global_load_dwordx4 v[146:149], v[56:57], off
	global_load_ushort v169, v[42:43], off offset:3840
	global_load_dwordx4 v[150:153], v[56:57], off offset:48
	global_load_ushort v170, v[58:59], off offset:3840
	global_load_dwordx4 v[96:99], v[86:87], off
	global_load_ushort v171, v[84:85], off offset:3840
	s_nop 0
	global_load_dwordx4 v[84:87], v[86:87], off offset:48
	s_nop 0
	global_load_ushort v172, v[156:157], off offset:3840
	global_load_dwordx4 v[56:59], v[162:163], off
	global_load_ushort v173, v[160:161], off offset:3840
	global_load_dwordx4 v[40:43], v[162:163], off offset:48
	s_nop 0
	global_load_ushort v162, v[164:165], off offset:3840
	global_load_ushort v163, v[4:5], off offset:3840
	global_load_dwordx4 v[8:11], v[6:7], off
	s_nop 0
	global_load_dwordx4 v[154:157], v[154:155], off
	s_nop 0
	global_load_dwordx4 v[4:7], v[158:159], off offset:16
	v_lshl_add_u64 v[158:159], s[82:83], 0, v[104:105]
	v_lshlrev_b32_e32 v104, 2, v166
	v_or3_b32 v160, v109, s8, v166
	v_lshl_add_u64 v[158:159], v[158:159], 0, v[104:105]
	v_ashrrev_i32_e32 v161, 31, v160
	global_load_dword v164, v[158:159], off
	global_load_dword v165, v[158:159], off offset:512
	global_load_dword v174, v[158:159], off offset:1024
	global_load_dword v175, v[158:159], off offset:1536
	global_load_dword v186, v[158:159], off offset:2048
	global_load_dword v187, v[158:159], off offset:2560
	global_load_dword v188, v[158:159], off offset:3072
	global_load_dword v189, v[158:159], off offset:3584
	v_add_co_u32_e32 v158, vcc, s2, v158
	v_lshl_add_u64 v[160:161], v[160:161], 2, s[50:51]
	s_nop 0
	v_addc_co_u32_e32 v159, vcc, 0, v159, vcc
	global_load_dword v160, v[160:161], off
	s_nop 0
	global_load_dword v161, v[158:159], off offset:512
	global_load_dword v190, v[158:159], off offset:1024
	global_load_dword v191, v[158:159], off offset:1536
	global_load_dword v192, v[158:159], off offset:2048
	global_load_dword v193, v[158:159], off offset:2560
	global_load_dword v194, v[158:159], off offset:3072
	global_load_dword v195, v[158:159], off offset:3584
	s_nop 0
	global_load_dword v158, v[158:159], off
	s_waitcnt vmcnt(0)
	s_barrier
	v_and_b32_e32 v252, 1, v210
	v_lshlrev_b32_e32 v252, 6, v252
	s_add_i32 s2, s20, s72
	s_cmpk_gt_i32 s2, 0x4ff
	s_cbranch_scc1 .Lwarm_done_g
	v_readfirstlane_b32 s3, v206
	s_nop 3
	s_lshr_b32 s3, s3, 6
	s_lshr_b32 vcc_lo, s3, 2
	s_and_b32 s3, s3, 3
	s_cmpk_lt_i32 s2, 0x300
	s_cselect_b32 s100, 1, 0
	s_movk_i32 s101, 0x300
	s_cselect_b32 s101, 0x100, s101
	s_sub_i32 s2, s2, s101
	s_lshl_b32 s2, s2, 1
	s_add_i32 s2, s2, vcc_lo
	s_sub_i32 vcc_hi, 3, s3
	s_cmp_eq_u32 vcc_lo, 0
	s_cselect_b32 vcc_hi, s3, vcc_hi
	s_lshr_b32 vcc_lo, s2, 7
	s_and_b32 s101, vcc_lo, 3
	s_lshr_b32 vcc_lo, vcc_lo, 2
	s_lshl_b32 vcc_lo, vcc_lo, 13
	s_and_b32 s2, s2, 0x7f
	s_lshl_b32 s2, s2, 6
	s_add_i32 s2, s2, vcc_lo
	s_lshl_b32 s3, s3, 4
	s_add_i32 s3, s3, s2
	s_lshl_b32 vcc_hi, vcc_hi, 4
	s_add_i32 vcc_hi, vcc_hi, s2
	s_lshl_b32 s2, s3, 6
	s_mul_i32 s3, s3, 0x1400
	s_mul_i32 vcc_hi, vcc_hi, 0x1400
	s_lshl_b32 vcc_lo, s101, 6
	s_cmp_eq_u32 s100, 1
	s_cbranch_scc0 .Lwarm_gla_g
	s_lshl_b32 vcc_lo, vcc_lo, 1
	s_add_u32 s100, s76, s3
	s_addc_u32 s101, s77, 0
	s_add_u32 s100, s100, vcc_lo
	s_addc_u32 s101, s101, 0
	global_load_dword v253, v252, s[100:101] offset:1536
	global_load_dword v253, v252, s[100:101] offset:2048
	s_add_u32 s100, s100, 0x1400
	s_addc_u32 s101, s101, 0
	global_load_dword v253, v252, s[100:101] offset:1536
	global_load_dword v253, v252, s[100:101] offset:2048
	s_add_u32 s100, s100, 0x1400
	s_addc_u32 s101, s101, 0
	global_load_dword v253, v252, s[100:101] offset:1536
	global_load_dword v253, v252, s[100:101] offset:2048
	s_add_u32 s100, s100, 0x1400
	s_addc_u32 s101, s101, 0
	global_load_dword v253, v252, s[100:101] offset:1536
	global_load_dword v253, v252, s[100:101] offset:2048
	s_add_u32 s100, s100, 0x1400
	s_addc_u32 s101, s101, 0
	global_load_dword v253, v252, s[100:101] offset:1536
	global_load_dword v253, v252, s[100:101] offset:2048
	s_add_u32 s100, s100, 0x1400
	s_addc_u32 s101, s101, 0
	global_load_dword v253, v252, s[100:101] offset:1536
	global_load_dword v253, v252, s[100:101] offset:2048
	s_add_u32 s100, s100, 0x1400
	s_addc_u32 s101, s101, 0
	global_load_dword v253, v252, s[100:101] offset:1536
	global_load_dword v253, v252, s[100:101] offset:2048
	s_add_u32 s100, s100, 0x1400
	s_addc_u32 s101, s101, 0
	global_load_dword v253, v252, s[100:101] offset:1536
	global_load_dword v253, v252, s[100:101] offset:2048
	s_add_u32 s100, s100, 0x1400
	s_addc_u32 s101, s101, 0
	global_load_dword v253, v252, s[100:101] offset:1536
	global_load_dword v253, v252, s[100:101] offset:2048
	s_add_u32 s100, s100, 0x1400
	s_addc_u32 s101, s101, 0
	global_load_dword v253, v252, s[100:101] offset:1536
	global_load_dword v253, v252, s[100:101] offset:2048
	s_add_u32 s100, s100, 0x1400
	s_addc_u32 s101, s101, 0
	global_load_dword v253, v252, s[100:101] offset:1536
	global_load_dword v253, v252, s[100:101] offset:2048
	s_add_u32 s100, s100, 0x1400
	s_addc_u32 s101, s101, 0
	global_load_dword v253, v252, s[100:101] offset:1536
	global_load_dword v253, v252, s[100:101] offset:2048
	s_add_u32 s100, s100, 0x1400
	s_addc_u32 s101, s101, 0
	global_load_dword v253, v252, s[100:101] offset:1536
	global_load_dword v253, v252, s[100:101] offset:2048
	s_add_u32 s100, s100, 0x1400
	s_addc_u32 s101, s101, 0
	global_load_dword v253, v252, s[100:101] offset:1536
	global_load_dword v253, v252, s[100:101] offset:2048
	s_add_u32 s100, s100, 0x1400
	s_addc_u32 s101, s101, 0
	global_load_dword v253, v252, s[100:101] offset:1536
	global_load_dword v253, v252, s[100:101] offset:2048
	s_add_u32 s100, s100, 0x1400
	s_addc_u32 s101, s101, 0
	global_load_dword v253, v252, s[100:101] offset:1536
	global_load_dword v253, v252, s[100:101] offset:2048
	s_add_u32 s100, s76, vcc_hi
	s_addc_u32 s101, s77, 0
	s_add_u32 s100, s100, vcc_lo
	s_addc_u32 s101, s101, 0
	global_load_dword v253, v252, s[100:101] offset:2560
	s_add_u32 s100, s100, 0x1400
	s_addc_u32 s101, s101, 0
	global_load_dword v253, v252, s[100:101] offset:2560
	s_add_u32 s100, s100, 0x1400
	s_addc_u32 s101, s101, 0
	global_load_dword v253, v252, s[100:101] offset:2560
	s_add_u32 s100, s100, 0x1400
	s_addc_u32 s101, s101, 0
	global_load_dword v253, v252, s[100:101] offset:2560
	s_add_u32 s100, s100, 0x1400
	s_addc_u32 s101, s101, 0
	global_load_dword v253, v252, s[100:101] offset:2560
	s_add_u32 s100, s100, 0x1400
	s_addc_u32 s101, s101, 0
	global_load_dword v253, v252, s[100:101] offset:2560
	s_add_u32 s100, s100, 0x1400
	s_addc_u32 s101, s101, 0
	global_load_dword v253, v252, s[100:101] offset:2560
	s_add_u32 s100, s100, 0x1400
	s_addc_u32 s101, s101, 0
	global_load_dword v253, v252, s[100:101] offset:2560
	s_add_u32 s100, s100, 0x1400
	s_addc_u32 s101, s101, 0
	global_load_dword v253, v252, s[100:101] offset:2560
	s_add_u32 s100, s100, 0x1400
	s_addc_u32 s101, s101, 0
	global_load_dword v253, v252, s[100:101] offset:2560
	s_add_u32 s100, s100, 0x1400
	s_addc_u32 s101, s101, 0
	global_load_dword v253, v252, s[100:101] offset:2560
	s_add_u32 s100, s100, 0x1400
	s_addc_u32 s101, s101, 0
	global_load_dword v253, v252, s[100:101] offset:2560
	s_add_u32 s100, s100, 0x1400
	s_addc_u32 s101, s101, 0
	global_load_dword v253, v252, s[100:101] offset:2560
	s_add_u32 s100, s100, 0x1400
	s_addc_u32 s101, s101, 0
	global_load_dword v253, v252, s[100:101] offset:2560
	s_add_u32 s100, s100, 0x1400
	s_addc_u32 s101, s101, 0
	global_load_dword v253, v252, s[100:101] offset:2560
	s_add_u32 s100, s100, 0x1400
	s_addc_u32 s101, s101, 0
	global_load_dword v253, v252, s[100:101] offset:2560
	s_branch .Lwarm_done_g
.Lwarm_gla_g:
	s_add_u32 s100, s76, s3
	s_addc_u32 s101, s77, 0
	s_add_u32 s100, s100, vcc_lo
	s_addc_u32 s101, s101, 0
	global_load_dword v253, v252, s[100:101] offset:3840
	s_add_u32 s100, s100, 0x1400
	s_addc_u32 s101, s101, 0
	global_load_dword v253, v252, s[100:101] offset:3840
	s_add_u32 s100, s100, 0x1400
	s_addc_u32 s101, s101, 0
	global_load_dword v253, v252, s[100:101] offset:3840
	s_add_u32 s100, s100, 0x1400
	s_addc_u32 s101, s101, 0
	global_load_dword v253, v252, s[100:101] offset:3840
	s_add_u32 s100, s100, 0x1400
	s_addc_u32 s101, s101, 0
	global_load_dword v253, v252, s[100:101] offset:3840
	s_add_u32 s100, s100, 0x1400
	s_addc_u32 s101, s101, 0
	global_load_dword v253, v252, s[100:101] offset:3840
	s_add_u32 s100, s100, 0x1400
	s_addc_u32 s101, s101, 0
	global_load_dword v253, v252, s[100:101] offset:3840
	s_add_u32 s100, s100, 0x1400
	s_addc_u32 s101, s101, 0
	global_load_dword v253, v252, s[100:101] offset:3840
	s_add_u32 s100, s100, 0x1400
	s_addc_u32 s101, s101, 0
	global_load_dword v253, v252, s[100:101] offset:3840
	s_add_u32 s100, s100, 0x1400
	s_addc_u32 s101, s101, 0
	global_load_dword v253, v252, s[100:101] offset:3840
	s_add_u32 s100, s100, 0x1400
	s_addc_u32 s101, s101, 0
	global_load_dword v253, v252, s[100:101] offset:3840
	s_add_u32 s100, s100, 0x1400
	s_addc_u32 s101, s101, 0
	global_load_dword v253, v252, s[100:101] offset:3840
	s_add_u32 s100, s100, 0x1400
	s_addc_u32 s101, s101, 0
	global_load_dword v253, v252, s[100:101] offset:3840
	s_add_u32 s100, s100, 0x1400
	s_addc_u32 s101, s101, 0
	global_load_dword v253, v252, s[100:101] offset:3840
	s_add_u32 s100, s100, 0x1400
	s_addc_u32 s101, s101, 0
	global_load_dword v253, v252, s[100:101] offset:3840
	s_add_u32 s100, s100, 0x1400
	s_addc_u32 s101, s101, 0
	global_load_dword v253, v252, s[100:101] offset:3840
	s_add_u32 s100, s76, vcc_hi
	s_addc_u32 s101, s77, 0
	s_add_u32 s100, s100, vcc_lo
	s_addc_u32 s101, s101, 0
	global_load_dword v253, v252, s[100:101] offset:3584
	s_add_u32 s100, s100, 0x1400
	s_addc_u32 s101, s101, 0
	global_load_dword v253, v252, s[100:101] offset:3584
	s_add_u32 s100, s100, 0x1400
	s_addc_u32 s101, s101, 0
	global_load_dword v253, v252, s[100:101] offset:3584
	s_add_u32 s100, s100, 0x1400
	s_addc_u32 s101, s101, 0
	global_load_dword v253, v252, s[100:101] offset:3584
	s_add_u32 s100, s100, 0x1400
	s_addc_u32 s101, s101, 0
	global_load_dword v253, v252, s[100:101] offset:3584
	s_add_u32 s100, s100, 0x1400
	s_addc_u32 s101, s101, 0
	global_load_dword v253, v252, s[100:101] offset:3584
	s_add_u32 s100, s100, 0x1400
	s_addc_u32 s101, s101, 0
	global_load_dword v253, v252, s[100:101] offset:3584
	s_add_u32 s100, s100, 0x1400
	s_addc_u32 s101, s101, 0
	global_load_dword v253, v252, s[100:101] offset:3584
	s_add_u32 s100, s100, 0x1400
	s_addc_u32 s101, s101, 0
	global_load_dword v253, v252, s[100:101] offset:3584
	s_add_u32 s100, s100, 0x1400
	s_addc_u32 s101, s101, 0
	global_load_dword v253, v252, s[100:101] offset:3584
	s_add_u32 s100, s100, 0x1400
	s_addc_u32 s101, s101, 0
	global_load_dword v253, v252, s[100:101] offset:3584
	s_add_u32 s100, s100, 0x1400
	s_addc_u32 s101, s101, 0
	global_load_dword v253, v252, s[100:101] offset:3584
	s_add_u32 s100, s100, 0x1400
	s_addc_u32 s101, s101, 0
	global_load_dword v253, v252, s[100:101] offset:3584
	s_add_u32 s100, s100, 0x1400
	s_addc_u32 s101, s101, 0
	global_load_dword v253, v252, s[100:101] offset:3584
	s_add_u32 s100, s100, 0x1400
	s_addc_u32 s101, s101, 0
	global_load_dword v253, v252, s[100:101] offset:3584
	s_add_u32 s100, s100, 0x1400
	s_addc_u32 s101, s101, 0
	global_load_dword v253, v252, s[100:101] offset:3584
	s_lshl_b32 vcc_lo, vcc_lo, 1
	s_addk_i32 vcc_lo, 0x800
	s_add_u32 s100, s76, s3
	s_addc_u32 s101, s77, 0
	s_add_u32 s100, s100, vcc_lo
	s_addc_u32 s101, s101, 0
	global_load_dword v253, v252, s[100:101] offset:2048
	s_add_u32 s100, s100, 0x1400
	s_addc_u32 s101, s101, 0
	global_load_dword v253, v252, s[100:101] offset:2048
	s_add_u32 s100, s100, 0x1400
	s_addc_u32 s101, s101, 0
	global_load_dword v253, v252, s[100:101] offset:2048
	s_add_u32 s100, s100, 0x1400
	s_addc_u32 s101, s101, 0
	global_load_dword v253, v252, s[100:101] offset:2048
	s_add_u32 s100, s100, 0x1400
	s_addc_u32 s101, s101, 0
	global_load_dword v253, v252, s[100:101] offset:2048
	s_add_u32 s100, s100, 0x1400
	s_addc_u32 s101, s101, 0
	global_load_dword v253, v252, s[100:101] offset:2048
	s_add_u32 s100, s100, 0x1400
	s_addc_u32 s101, s101, 0
	global_load_dword v253, v252, s[100:101] offset:2048
	s_add_u32 s100, s100, 0x1400
	s_addc_u32 s101, s101, 0
	global_load_dword v253, v252, s[100:101] offset:2048
	s_add_u32 s100, s100, 0x1400
	s_addc_u32 s101, s101, 0
	global_load_dword v253, v252, s[100:101] offset:2048
	s_add_u32 s100, s100, 0x1400
	s_addc_u32 s101, s101, 0
	global_load_dword v253, v252, s[100:101] offset:2048
	s_add_u32 s100, s100, 0x1400
	s_addc_u32 s101, s101, 0
	global_load_dword v253, v252, s[100:101] offset:2048
	s_add_u32 s100, s100, 0x1400
	s_addc_u32 s101, s101, 0
	global_load_dword v253, v252, s[100:101] offset:2048
	s_add_u32 s100, s100, 0x1400
	s_addc_u32 s101, s101, 0
	global_load_dword v253, v252, s[100:101] offset:2048
	s_add_u32 s100, s100, 0x1400
	s_addc_u32 s101, s101, 0
	global_load_dword v253, v252, s[100:101] offset:2048
	s_add_u32 s100, s100, 0x1400
	s_addc_u32 s101, s101, 0
	global_load_dword v253, v252, s[100:101] offset:2048
	s_add_u32 s100, s100, 0x1400
	s_addc_u32 s101, s101, 0
	global_load_dword v253, v252, s[100:101] offset:2048
	s_add_u32 s100, s68, s2
	s_addc_u32 s101, s69, 0
	s_add_u32 s100, s100, 0xdae0000
	s_addc_u32 s101, s101, 0
	global_load_dword v253, v252, s[100:101] offset:0
	global_load_dword v253, v252, s[100:101] offset:128
	global_load_dword v253, v252, s[100:101] offset:256
	global_load_dword v253, v252, s[100:101] offset:384
	global_load_dword v253, v252, s[100:101] offset:512
	global_load_dword v253, v252, s[100:101] offset:640
	global_load_dword v253, v252, s[100:101] offset:768
	global_load_dword v253, v252, s[100:101] offset:896
.Lwarm_done_g:
	s_mov_b32 s3, 0xbfb8aa3b
	s_mov_b32 s2, 0x3d800000
	v_cmp_gt_u32_sdwa s[4:5], v115, v219 src0_sel:BYTE_0 src1_sel:DWORD
	v_mul_f32_e32 v105, v155, v165
	v_fmac_f32_e32 v105, v154, v164
	v_fmac_f32_e32 v105, v156, v174
	v_fmac_f32_e32 v105, v157, v175
	v_fmac_f32_e32 v105, v122, v186
	v_mul_f32_e32 v119, v119, v161
	v_fmac_f32_e32 v105, v123, v187
	v_mul_f32_e32 v81, v81, v165
	v_fmac_f32_e32 v105, v124, v188
	v_fmac_f32_e32 v81, v80, v164
	v_mul_f32_e32 v73, v73, v161
	v_fmac_f32_e32 v105, v125, v189
	v_fmac_f32_e32 v119, v118, v158
	v_fmac_f32_e32 v119, v120, v190
	v_fmac_f32_e32 v119, v121, v191
	v_fmac_f32_e32 v119, v142, v192
	v_fmac_f32_e32 v119, v143, v193
	v_fmac_f32_e32 v119, v144, v194
	v_fmac_f32_e32 v81, v82, v174
	v_fmac_f32_e32 v73, v72, v158
	v_mul_f32_e32 v53, v53, v165
	v_add_f32_e32 v105, v105, v160
	v_fmac_f32_e32 v119, v145, v195
	v_fmac_f32_e32 v81, v83, v175
	v_fmac_f32_e32 v73, v74, v190
	v_fmac_f32_e32 v53, v52, v164
	v_mul_f32_e32 v45, v45, v161
	v_add_f32_e32 v118, v119, v105
	v_fmac_f32_e32 v81, v76, v186
	v_fmac_f32_e32 v73, v75, v191
	v_fmac_f32_e32 v53, v54, v174
	v_fmac_f32_e32 v45, v44, v158
	v_mul_f32_e64 v105, |v118|, s3
	v_fmac_f32_e32 v81, v77, v187
	v_fmac_f32_e32 v73, v68, v192
	v_fmac_f32_e32 v53, v55, v175
	v_fmac_f32_e32 v45, v46, v190
	v_exp_f32_e32 v105, v105
	v_fmac_f32_e32 v81, v78, v188
	v_fmac_f32_e32 v73, v69, v193
	v_fmac_f32_e32 v53, v48, v186
	v_fmac_f32_e32 v45, v47, v191
	v_fmac_f32_e32 v81, v79, v189
	v_fmac_f32_e32 v73, v70, v194
	v_fmac_f32_e32 v53, v49, v187
	v_fmac_f32_e32 v45, v36, v192
	v_mul_f32_e32 v121, v139, v165
	v_add_f32_e32 v76, v81, v160
	v_fmac_f32_e32 v73, v71, v195
	v_fmac_f32_e32 v53, v50, v188
	v_fmac_f32_e32 v45, v37, v193
	v_fmac_f32_e32 v121, v138, v164
	v_mul_f32_e32 v122, v131, v161
	v_add_f32_e32 v68, v73, v76
	v_fmac_f32_e32 v53, v51, v189
	v_fmac_f32_e32 v45, v38, v194
	v_add_f32_e32 v105, 1.0, v105
	v_fmac_f32_e32 v121, v140, v174
	v_fmac_f32_e32 v122, v130, v158
	v_mul_f32_e64 v69, |v68|, s3
	v_add_f32_e32 v48, v53, v160
	v_fmac_f32_e32 v45, v39, v195
	v_log_f32_e32 v120, v105
	v_fmac_f32_e32 v121, v141, v175
	v_fmac_f32_e32 v122, v132, v190
	v_exp_f32_e32 v69, v69
	v_add_f32_e32 v36, v45, v48
	v_fmac_f32_e32 v121, v134, v186
	v_fmac_f32_e32 v122, v133, v191
	v_mul_f32_e64 v37, |v36|, s3
	v_fmac_f32_e32 v121, v135, v187
	v_fmac_f32_e32 v122, v126, v192
	v_exp_f32_e32 v37, v37
	v_min_f32_e32 v118, 0, v118
	v_fmac_f32_e32 v121, v136, v188
	v_fmac_f32_e32 v122, v127, v193
	v_fmac_f32_e32 v118, 0xbf317218, v120
	v_fmac_f32_e32 v121, v137, v189
	v_fmac_f32_e32 v122, v128, v194
	v_mul_u32_u24_e32 v123, 0x108, v103
	v_add_f32_e32 v69, 1.0, v69
	v_lshrrev_b32_e32 v119, 8, v106
	v_add_f32_e32 v121, v121, v160
	v_fmac_f32_e32 v122, v129, v195
	v_fma_f32 v118, v118, s2, 0
	v_add_lshl_u32 v123, v123, v166, 2
	s_mov_b32 s2, 0xd800
	v_log_f32_e32 v69, v69
	v_lshlrev_b32_e32 v120, 16, v168
	v_add_f32_e32 v121, v122, v121
	v_mad_i32_i24 v123, v119, s2, v123
	v_add_f32_e32 v37, 1.0, v37
	v_mul_f32_e64 v122, |v121|, s3
	ds_write2st64_b32 v123, v118, v120 offset1:68
	v_min_f32_e32 v120, 0, v121
	v_mul_f32_e32 v121, v147, v165
	v_log_f32_e32 v37, v37
	v_fmac_f32_e32 v121, v146, v164
	v_mul_f32_e32 v89, v89, v161
	v_min_f32_e32 v68, 0, v68
	v_fmac_f32_e32 v121, v148, v174
	v_fmac_f32_e32 v89, v88, v158
	v_fmac_f32_e32 v68, 0xbf317218, v69
	v_mul_f32_e32 v69, v97, v165
	v_fmac_f32_e32 v121, v149, v175
	v_fmac_f32_e32 v89, v90, v190
	v_fmac_f32_e32 v69, v96, v164
	v_mul_f32_e32 v61, v61, v161
	v_min_f32_e32 v36, 0, v36
	v_fmac_f32_e32 v121, v92, v186
	v_fmac_f32_e32 v89, v91, v191
	v_fmac_f32_e32 v69, v98, v174
	v_fmac_f32_e32 v61, v60, v158
	v_fmac_f32_e32 v36, 0xbf317218, v37
	v_mul_f32_e32 v37, v57, v165
	v_fmac_f32_e32 v121, v93, v187
	v_fmac_f32_e32 v89, v150, v192
	v_fmac_f32_e32 v69, v99, v175
	v_fmac_f32_e32 v61, v62, v190
	v_fmac_f32_e32 v37, v56, v164
	v_mul_f32_e32 v29, v29, v161
	v_mul_f32_e32 v25, v25, v165
	v_fmac_f32_e32 v121, v94, v188
	v_fmac_f32_e32 v89, v151, v193
	v_fmac_f32_e32 v69, v64, v186
	v_fmac_f32_e32 v61, v63, v191
	v_fmac_f32_e32 v37, v58, v174
	v_fmac_f32_e32 v29, v28, v158
	v_fmac_f32_e32 v25, v24, v164
	v_mul_f32_e32 v17, v17, v161
	v_fmac_f32_e32 v121, v95, v189
	v_fmac_f32_e32 v89, v152, v194
	v_fmac_f32_e32 v69, v65, v187
	v_fmac_f32_e32 v61, v84, v192
	v_fmac_f32_e32 v37, v59, v175
	v_fmac_f32_e32 v29, v30, v190
	v_fmac_f32_e32 v25, v26, v174
	v_fmac_f32_e32 v17, v16, v158
	v_add_f32_e32 v92, v121, v160
	v_fmac_f32_e32 v89, v153, v195
	v_fmac_f32_e32 v69, v66, v188
	v_fmac_f32_e32 v61, v85, v193
	v_fmac_f32_e32 v37, v32, v186
	v_fmac_f32_e32 v29, v31, v191
	v_fmac_f32_e32 v25, v27, v175
	v_fmac_f32_e32 v17, v18, v190
	v_add_f32_e32 v88, v89, v92
	v_fmac_f32_e32 v69, v67, v189
	v_fmac_f32_e32 v61, v86, v194
	v_fmac_f32_e32 v37, v33, v187
	v_fmac_f32_e32 v29, v40, v192
	v_fmac_f32_e32 v25, v20, v186
	v_fmac_f32_e32 v17, v19, v191
	v_exp_f32_e32 v122, v122
	v_mul_f32_e64 v89, |v88|, s3
	v_add_f32_e32 v64, v69, v160
	v_fmac_f32_e32 v61, v87, v195
	v_fmac_f32_e32 v37, v34, v188
	v_fmac_f32_e32 v29, v41, v193
	v_fmac_f32_e32 v25, v21, v187
	v_fmac_f32_e32 v17, v12, v192
	v_exp_f32_e32 v89, v89
	v_add_f32_e32 v60, v61, v64
	v_fmac_f32_e32 v37, v35, v189
	v_fmac_f32_e32 v29, v42, v194
	v_fmac_f32_e32 v25, v22, v188
	v_fmac_f32_e32 v17, v13, v193
	v_mul_f32_e64 v61, |v60|, s3
	v_add_f32_e32 v32, v37, v160
	v_fmac_f32_e32 v29, v43, v195
	v_fmac_f32_e32 v25, v23, v189
	v_fmac_f32_e32 v17, v14, v194
	v_exp_f32_e32 v61, v61
	v_add_f32_e32 v28, v29, v32
	v_add_f32_e32 v20, v25, v160
	v_fmac_f32_e32 v17, v15, v195
	v_add_f32_e32 v122, 1.0, v122
	v_mul_f32_e64 v29, |v28|, s3
	v_add_f32_e32 v12, v17, v20
	v_log_f32_e32 v122, v122
	v_add_f32_e32 v89, 1.0, v89
	v_exp_f32_e32 v29, v29
	v_mul_f32_e64 v13, |v12|, s3
	v_log_f32_e32 v89, v89
	v_exp_f32_e32 v13, v13
	v_add_f32_e32 v61, 1.0, v61
	v_log_f32_e32 v61, v61
	v_fmac_f32_e32 v120, 0xbf317218, v122
	v_mul_u32_u24_e32 v91, 33, v167
	v_min_f32_e32 v88, 0, v88
	v_add_f32_e32 v29, 1.0, v29
	v_fmac_f32_e32 v118, 0x3d800000, v120
	v_add_lshl_u32 v91, v91, v166, 2
	v_fmac_f32_e32 v88, 0xbf317218, v89
	v_log_f32_e32 v29, v29
	v_add_f32_e32 v13, 1.0, v13
	v_mad_i32_i24 v91, v119, s2, v91
	v_fmamk_f32 v71, v88, 0x3d800000, v118
	v_min_f32_e32 v60, 0, v60
	v_log_f32_e32 v13, v13
	ds_write2_b32 v91, v118, v71 offset1:33
	v_fmac_f32_e32 v71, 0x3d800000, v68
	v_fmac_f32_e32 v60, 0xbf317218, v61
	v_lshlrev_b32_e32 v90, 16, v169
	v_lshlrev_b32_e32 v70, 16, v170
	v_add_u32_e32 v72, 0x4400, v91
	v_fmamk_f32 v39, v60, 0x3d800000, v71
	v_min_f32_e32 v28, 0, v28
	ds_write2_b32 v72, v90, v70 offset1:33
	v_lshlrev_b32_e32 v62, 16, v171
	v_lshlrev_b32_e32 v38, 16, v172
	ds_write2_b32 v91, v71, v39 offset0:66 offset1:99
	ds_write2_b32 v72, v62, v38 offset0:66 offset1:99
	v_fmac_f32_e32 v39, 0x3d800000, v36
	v_fmac_f32_e32 v28, 0xbf317218, v29
	v_min_f32_e32 v12, 0, v12
	v_fmamk_f32 v15, v28, 0x3d800000, v39
	v_fmac_f32_e32 v12, 0xbf317218, v13
	v_mul_i32_i24_e32 v105, 0xd800, v119
	v_lshlrev_b32_e32 v30, 16, v173
	v_lshlrev_b32_e32 v14, 16, v162
	ds_write2_b32 v91, v39, v15 offset0:132 offset1:165
	ds_write2_b32 v72, v30, v14 offset0:132 offset1:165
	v_fmac_f32_e32 v15, 0x3d800000, v12
	v_lshlrev_b32_e32 v12, 8, v103
	v_or3_b32 v12, v105, v12, v104
	v_lshlrev_b32_e32 v13, 16, v163
	ds_write_b32 v91, v15 offset:792
	ds_write_b32 v91, v13 offset:18200
	ds_write_b32 v12, v15 offset:53248
	v_mul_u32_u24_e32 v12, 0x48, v117
	v_lshlrev_b32_e32 v12, 1, v12
	v_mad_i32_i24 v12, v119, s2, v12
	v_mov_b32_e32 v106, 0
	v_lshl_or_b32 v12, v116, 1, v12
	ds_write_b16 v12, v8 offset:34816
	ds_write_b16_d16_hi v12, v8 offset:34960
	ds_write_b16 v12, v9 offset:35104
	ds_write_b16_d16_hi v12, v9 offset:35248
	ds_write_b16 v12, v10 offset:35392
	ds_write_b16_d16_hi v12, v10 offset:35536
	ds_write_b16 v12, v11 offset:35680
	ds_write_b16_d16_hi v12, v11 offset:35824
	ds_write_b16 v12, v4 offset:35968
	ds_write_b16_d16_hi v12, v4 offset:36112
	ds_write_b16 v12, v5 offset:36256
	ds_write_b16_d16_hi v12, v5 offset:36400
	ds_write_b16 v12, v6 offset:36544
	ds_write_b16_d16_hi v12, v6 offset:36688
	ds_write_b16 v12, v7 offset:36832
	ds_write_b16_d16_hi v12, v7 offset:36976
	s_waitcnt lgkmcnt(0)
	s_barrier
	s_and_saveexec_b64 s[2:3], s[4:5]
	s_cbranch_execz .LBB0_196
	s_mov_b32 s4, 0xd000
	v_add3_u32 v4, v105, v104, s4
	v_mov_b32_e32 v106, 0
	ds_read_b32 v220, v4
	ds_read_b32 v221, v4 offset:256
	ds_read_b32 v222, v4 offset:512
	ds_read_b32 v223, v4 offset:768
	ds_read_b32 v224, v4 offset:1024
	ds_read_b32 v225, v4 offset:1280
	ds_read_b32 v226, v4 offset:1536
	s_waitcnt lgkmcnt(0)
	v_add_f32_e32 v106, v106, v220
	v_cmp_lt_u32_e32 vcc, 1, v103
	s_nop 1
	v_cndmask_b32_e32 v221, 0, v221, vcc
	v_add_f32_e32 v106, v106, v221
	v_cmp_lt_u32_e32 vcc, 2, v103
	s_nop 1
	v_cndmask_b32_e32 v222, 0, v222, vcc
	v_add_f32_e32 v106, v106, v222
	v_cmp_lt_u32_e32 vcc, 3, v103
	s_nop 1
	v_cndmask_b32_e32 v223, 0, v223, vcc
	v_add_f32_e32 v106, v106, v223
	v_cmp_lt_u32_e32 vcc, 4, v103
	s_nop 1
	v_cndmask_b32_e32 v224, 0, v224, vcc
	v_add_f32_e32 v106, v106, v224
	v_cmp_lt_u32_e32 vcc, 5, v103
	s_nop 1
	v_cndmask_b32_e32 v225, 0, v225, vcc
	v_add_f32_e32 v106, v106, v225
	v_cmp_lt_u32_e32 vcc, 6, v103
	s_nop 1
	v_cndmask_b32_e32 v226, 0, v226, vcc
	v_add_f32_e32 v106, v106, v226
	v_mov_b32_e32 v103, 0

.LBB0_200:
	s_or_b64 exec, exec, s[2:3]
	s_movk_i32 s2, 0x840
	v_mad_u32_u24 v12, v108, s2, v105
	v_add_u32_e32 v4, 0xffffff7c, v12
	v_cmp_eq_u32_e64 s[36:37], 0, v108
	v_cmp_ne_u32_e32 vcc, 0, v108
	v_mov_b32_e32 v25, 0
	v_lshl_add_u32 v14, v15, 2, v4
	v_mov_b32_e32 v26, 0
	s_and_saveexec_b64 s[2:3], vcc
	ds_read_b32 v26, v14
	s_or_b64 exec, exec, s[2:3]
	v_lshlrev_b32_e32 v13, 2, v15
	s_and_saveexec_b64 s[2:3], vcc
	s_movk_i32 s4, 0xff80
	v_add3_u32 v4, v12, v13, s4
	ds_read_b32 v25, v4
	s_or_b64 exec, exec, s[2:3]
	v_mul_u32_u24_e32 v4, 0x84, v110
	v_add3_u32 v11, v105, v4, v13
	ds_read2_b32 v[4:5], v11 offset1:1
	v_mov_b32_e32 v27, 0
	v_mov_b32_e32 v28, 0
	s_and_saveexec_b64 s[2:3], vcc
	ds_read_b32 v28, v14 offset:8
	s_or_b64 exec, exec, s[2:3]
	s_and_saveexec_b64 s[2:3], vcc
	s_movk_i32 s4, 0xff88
	v_add3_u32 v6, v12, v13, s4
	ds_read_b32 v27, v6
	s_or_b64 exec, exec, s[2:3]
	ds_read2_b32 v[6:7], v11 offset0:2 offset1:3
	v_mov_b32_e32 v20, 0
	v_mov_b32_e32 v21, 0
	s_and_saveexec_b64 s[2:3], vcc
	ds_read_b32 v21, v14 offset:16
	s_or_b64 exec, exec, s[2:3]
	s_and_saveexec_b64 s[2:3], vcc
	s_movk_i32 s4, 0xff90
	v_add3_u32 v8, v12, v13, s4
	ds_read_b32 v20, v8
	s_or_b64 exec, exec, s[2:3]
	ds_read2_b32 v[8:9], v11 offset0:4 offset1:5
	v_mov_b32_e32 v22, 0
	v_mov_b32_e32 v23, 0
	s_and_saveexec_b64 s[2:3], vcc
	ds_read_b32 v23, v14 offset:24
	s_or_b64 exec, exec, s[2:3]
	s_and_saveexec_b64 s[2:3], vcc
	s_movk_i32 s4, 0xff98
	v_add3_u32 v12, v12, v13, s4
	ds_read_b32 v22, v12
	s_or_b64 exec, exec, s[2:3]
	s_waitcnt lgkmcnt(2)
	v_sub_f32_e32 v12, v4, v26
	v_sub_f32_e32 v13, v5, v25
	v_mul_f32_e32 v4, 0x3fb8aa3b, v4
	v_mul_f32_e32 v5, 0x3fb8aa3b, v5
	v_exp_f32_e32 v4, v4
	v_exp_f32_e32 v5, v5
	v_mul_f32_e32 v12, 0x3fb8aa3b, v12
	v_mul_f32_e32 v13, 0x3fb8aa3b, v13
	v_exp_f32_e32 v12, v12
	v_exp_f32_e32 v13, v13
	v_lshlrev_b32_e32 v16, 16, v0
	v_and_b32_e32 v17, 0xffff0000, v0
	s_mov_b32 s2, 0x3e3504f3
	v_pk_mul_f32 v[16:17], v[16:17], s[2:3] op_sel_hi:[1,0]
	s_movk_i32 s4, 0x300
	v_pk_mul_f32 v[4:5], v[16:17], v[4:5]
	v_pk_mul_f32 v[12:13], v[16:17], v[12:13]
	v_cvt_pk_bf16_f32 v4, v4, v5
	s_waitcnt lgkmcnt(1)
	v_sub_f32_e32 v5, v6, v28
	v_mul_f32_e32 v5, 0x3fb8aa3b, v5
	v_cvt_pk_bf16_f32 v0, v12, v13
	v_exp_f32_e32 v12, v5
	v_sub_f32_e32 v5, v7, v27
	v_mul_f32_e32 v5, 0x3fb8aa3b, v5
	v_exp_f32_e32 v13, v5
	v_mul_f32_e32 v5, 0x3fb8aa3b, v6
	v_exp_f32_e32 v6, v5
	v_mul_f32_e32 v5, 0x3fb8aa3b, v7
	v_exp_f32_e32 v7, v5
	v_lshlrev_b32_e32 v16, 16, v1
	v_and_b32_e32 v17, 0xffff0000, v1
	v_pk_mul_f32 v[16:17], v[16:17], s[2:3] op_sel_hi:[1,0]
	v_or_b32_e32 v31, 2, v24
	v_pk_mul_f32 v[6:7], v[16:17], v[6:7]
	v_pk_mul_f32 v[12:13], v[16:17], v[12:13]
	v_cvt_pk_bf16_f32 v5, v6, v7
	s_waitcnt lgkmcnt(0)
	v_sub_f32_e32 v6, v8, v21
	v_sub_f32_e32 v7, v9, v20
	v_mul_f32_e32 v6, 0x3fb8aa3b, v6
	v_mul_f32_e32 v7, 0x3fb8aa3b, v7
	v_exp_f32_e32 v6, v6
	v_exp_f32_e32 v7, v7
	v_mul_f32_e32 v8, 0x3fb8aa3b, v8
	v_mul_f32_e32 v9, 0x3fb8aa3b, v9
	v_exp_f32_e32 v8, v8
	v_exp_f32_e32 v9, v9
	v_cvt_pk_bf16_f32 v1, v12, v13
	v_lshlrev_b32_e32 v12, 16, v2
	v_and_b32_e32 v13, 0xffff0000, v2
	v_pk_mul_f32 v[12:13], v[12:13], s[2:3] op_sel_hi:[1,0]
	v_lshlrev_b32_e32 v16, 16, v3
	v_pk_mul_f32 v[6:7], v[12:13], v[6:7]
	v_and_b32_e32 v17, 0xffff0000, v3
	v_cvt_pk_bf16_f32 v2, v6, v7
	v_pk_mul_f32 v[6:7], v[12:13], v[8:9]
	ds_read2_b32 v[8:9], v11 offset0:6 offset1:7
	v_cvt_pk_bf16_f32 v6, v6, v7
	v_pk_mul_f32 v[16:17], v[16:17], s[2:3] op_sel_hi:[1,0]
	v_or_b32_e32 v30, 3, v24
	s_waitcnt lgkmcnt(0)
	v_sub_f32_e32 v7, v8, v23
	v_mul_f32_e32 v7, 0x3fb8aa3b, v7
	v_exp_f32_e32 v12, v7
	v_sub_f32_e32 v7, v9, v22
	v_mul_f32_e32 v7, 0x3fb8aa3b, v7
	v_exp_f32_e32 v13, v7
	v_mul_f32_e32 v7, 0x3fb8aa3b, v8
	v_exp_f32_e32 v8, v7
	v_mul_f32_e32 v7, 0x3fb8aa3b, v9
	v_exp_f32_e32 v9, v7
	v_pk_mul_f32 v[12:13], v[16:17], v[12:13]
	v_pk_mul_f32 v[8:9], v[16:17], v[8:9]
	s_nop 0
	v_cvt_pk_bf16_f32 v7, v8, v9
	v_mov_b64_e32 v[8:9], s[68:69]
	v_mad_u64_u32 v[8:9], s[2:3], v100, s4, v[8:9]
	v_cvt_pk_bf16_f32 v3, v12, v13
	v_mov_b32_e32 v12, v9
	v_mad_u64_u32 v[12:13], s[2:3], v101, s4, v[12:13]
	v_mov_b32_e32 v9, v12
	v_lshlrev_b32_e32 v12, 1, v109
	v_mov_b32_e32 v13, v177
	v_lshl_add_u64 v[8:9], v[8:9], 0, v[12:13]
	v_lshlrev_b32_e32 v12, 1, v15
	v_lshl_add_u64 v[8:9], v[8:9], 0, v[12:13]
	s_mov_b32 s2, 0xece4000
	v_add_co_u32_e64 v8, s[38:39], s2, v8
	s_nop 1
	v_addc_co_u32_e64 v9, s[38:39], 0, v9, s[38:39]
	global_store_dwordx4 v[8:9], v[4:7], off offset:512 sc1
	s_nop 1
	v_mad_u32_u24 v4, v107, 33, v15
	v_lshl_add_u32 v29, v4, 2, v105
	ds_read2_b32 v[4:5], v29 offset1:1
	v_add_u32_e32 v6, 0x4400, v29
	ds_read2_b32 v[6:7], v6 offset1:1
	s_waitcnt lgkmcnt(1)
	v_sub_f32_e32 v4, v26, v4
	v_sub_f32_e32 v5, v25, v5
	v_min_f32_e32 v4, 0x42a00000, v4
	v_min_f32_e32 v5, 0x42a00000, v5
	v_mul_f32_e32 v4, 0x3fb8aa3b, v4
	v_mul_f32_e32 v5, 0x3fb8aa3b, v5
	v_exp_f32_e32 v4, v4
	v_exp_f32_e32 v5, v5
	s_waitcnt lgkmcnt(0)
	v_pk_mul_f32 v[4:5], v[6:7], v[4:5]
	ds_read2_b32 v[6:7], v29 offset0:2 offset1:3
	v_cvt_pk_bf16_f32 v4, v4, v5
	v_add_u32_e32 v5, 0x4408, v29
	ds_read2_b32 v[8:9], v5 offset1:1
	s_waitcnt lgkmcnt(1)
	v_sub_f32_e32 v6, v28, v6
	v_sub_f32_e32 v7, v27, v7
	v_min_f32_e32 v6, 0x42a00000, v6
	v_min_f32_e32 v7, 0x42a00000, v7
	v_mul_f32_e32 v6, 0x3fb8aa3b, v6
	v_mul_f32_e32 v7, 0x3fb8aa3b, v7
	v_exp_f32_e32 v6, v6
	v_exp_f32_e32 v7, v7
	s_waitcnt lgkmcnt(0)
	v_pk_mul_f32 v[6:7], v[8:9], v[6:7]
	s_nop 0
	v_cvt_pk_bf16_f32 v5, v6, v7
	ds_read2_b32 v[6:7], v29 offset0:4 offset1:5
	v_add_u32_e32 v8, 0x4410, v29
	ds_read2_b32 v[8:9], v8 offset1:1
	s_waitcnt lgkmcnt(1)
	v_sub_f32_e32 v6, v21, v6
	v_sub_f32_e32 v7, v20, v7
	v_min_f32_e32 v6, 0x42a00000, v6
	v_min_f32_e32 v7, 0x42a00000, v7
	v_mul_f32_e32 v6, 0x3fb8aa3b, v6
	v_mul_f32_e32 v7, 0x3fb8aa3b, v7
	v_exp_f32_e32 v6, v6
	v_exp_f32_e32 v7, v7
	s_waitcnt lgkmcnt(0)
	v_pk_mul_f32 v[6:7], v[8:9], v[6:7]
	ds_read2_b32 v[8:9], v29 offset0:6 offset1:7
	v_cvt_pk_bf16_f32 v6, v6, v7
	v_add_u32_e32 v7, 0x4418, v29
	ds_read2_b32 v[12:13], v7 offset1:1
	s_waitcnt lgkmcnt(1)
	v_sub_f32_e32 v8, v23, v8
	v_sub_f32_e32 v9, v22, v9
	v_min_f32_e32 v8, 0x42a00000, v8
	v_min_f32_e32 v9, 0x42a00000, v9
	v_mul_f32_e32 v8, 0x3fb8aa3b, v8
	v_mul_f32_e32 v9, 0x3fb8aa3b, v9
	v_exp_f32_e32 v8, v8
	v_exp_f32_e32 v9, v9
	s_waitcnt lgkmcnt(0)
	v_pk_mul_f32 v[8:9], v[12:13], v[8:9]
	s_nop 0
	v_cvt_pk_bf16_f32 v7, v8, v9
	v_mov_b32_e32 v8, 0
	s_nop 0
	v_mfma_f32_16x16x32_bf16 v[4:7], v[4:7], v[0:3], 0
	s_and_saveexec_b64 s[2:3], s[36:37]
	v_cmp_gt_u32_e64 s[36:37], v24, v107
	s_nop 5
	v_cndmask_b32_e64 v9, v4, 0, s[36:37]
	v_cmp_lt_u32_e64 s[36:37], v24, v107
	s_nop 1
	v_cndmask_b32_e64 v4, v9, v4, s[36:37]
	v_cndmask_b32_e64 v5, 0, v5, s[36:37]
	v_cmp_le_u32_e64 s[36:37], v31, v107
	s_nop 1
	v_cndmask_b32_e64 v6, 0, v6, s[36:37]
	v_cmp_le_u32_e64 s[36:37], v30, v107
	s_nop 1
	v_cndmask_b32_e64 v7, 0, v7, s[36:37]
	s_or_b64 exec, exec, s[2:3]
	v_mov_b32_e32 v16, 0
	v_mov_b32_e32 v17, 0
	v_mov_b32_e32 v18, 0
	v_mov_b32_e32 v19, 0
	s_and_saveexec_b64 s[4:5], vcc
	s_cbranch_execz .LBB0_222
	v_mad_u32_u24 v9, v10, 33, v15
	v_lshl_add_u32 v9, v9, 2, v105
	ds_read2_b32 v[200:201], v9 offset1:1
	v_add_u32_e32 v251, 0x4400, v9
	ds_read2_b32 v[202:203], v251 offset1:1
	ds_read2_b32 v[204:205], v9 offset0:2 offset1:3
	v_add_u32_e32 v250, 0x4408, v9
	ds_read2_b32 v[220:221], v250 offset1:1
	ds_read2_b32 v[222:223], v9 offset0:4 offset1:5
	v_add_u32_e32 v249, 0x4410, v9
	ds_read2_b32 v[224:225], v249 offset1:1
	ds_read2_b32 v[226:227], v9 offset0:6 offset1:7
	v_add_u32_e32 v248, 0x4418, v9
	ds_read2_b32 v[228:229], v248 offset1:1
	v_cmp_eq_u32_e32 vcc, 1, v108
	s_waitcnt lgkmcnt(1)
	v_sub_f32_e32 v10, v26, v200
	v_sub_f32_e32 v11, v25, v201
	v_min_f32_e32 v10, 0x42a00000, v10
	v_min_f32_e32 v11, 0x42a00000, v11
	v_mul_f32_e32 v10, 0x3fb8aa3b, v10
	v_mul_f32_e32 v11, 0x3fb8aa3b, v11
	v_exp_f32_e32 v10, v10
	v_exp_f32_e32 v11, v11
	s_waitcnt lgkmcnt(0)
	v_pk_mul_f32 v[10:11], v[202:203], v[10:11]
	v_cvt_pk_bf16_f32 v10, v10, v11
	s_waitcnt lgkmcnt(1)
	v_sub_f32_e32 v12, v28, v204
	v_sub_f32_e32 v13, v27, v205
	v_min_f32_e32 v12, 0x42a00000, v12
	v_min_f32_e32 v13, 0x42a00000, v13
	v_mul_f32_e32 v12, 0x3fb8aa3b, v12
	v_mul_f32_e32 v13, 0x3fb8aa3b, v13
	v_exp_f32_e32 v12, v12
	v_exp_f32_e32 v13, v13
	s_waitcnt lgkmcnt(0)
	v_pk_mul_f32 v[12:13], v[220:221], v[12:13]
	s_nop 0
	v_cvt_pk_bf16_f32 v11, v12, v13
	s_waitcnt lgkmcnt(1)
	v_sub_f32_e32 v12, v21, v222
	v_sub_f32_e32 v13, v20, v223
	v_min_f32_e32 v12, 0x42a00000, v12
	v_min_f32_e32 v13, 0x42a00000, v13
	v_mul_f32_e32 v12, 0x3fb8aa3b, v12
	v_mul_f32_e32 v13, 0x3fb8aa3b, v13
	v_exp_f32_e32 v12, v12
	v_exp_f32_e32 v13, v13
	s_waitcnt lgkmcnt(0)
	v_pk_mul_f32 v[12:13], v[224:225], v[12:13]
	v_cvt_pk_bf16_f32 v12, v12, v13
	s_waitcnt lgkmcnt(1)
	v_sub_f32_e32 v9, v23, v226
	v_min_f32_e32 v9, 0x42a00000, v9
	v_mul_f32_e32 v9, 0x3fb8aa3b, v9
	v_exp_f32_e32 v16, v9
	v_sub_f32_e32 v9, v22, v227
	v_min_f32_e32 v9, 0x42a00000, v9
	v_mul_f32_e32 v9, 0x3fb8aa3b, v9
	v_exp_f32_e32 v17, v9
	s_waitcnt lgkmcnt(0)
	v_pk_mul_f32 v[16:17], v[228:229], v[16:17]
	s_nop 0
	v_cvt_pk_bf16_f32 v13, v16, v17
	s_nop 1
	v_mfma_f32_16x16x32_bf16 v[16:19], v[10:13], v[0:3], 0
	s_and_saveexec_b64 s[2:3], vcc
	s_cbranch_execz .LBB0_221
	v_cmp_gt_u32_e32 vcc, v24, v107
	s_nop 4
	v_cndmask_b32_e32 v9, v18, v18, vcc
	v_cndmask_b32_e32 v10, v19, v19, vcc
	v_cndmask_b32_e64 v11, v16, 0, vcc
	v_cmp_lt_u32_e32 vcc, v24, v107
	s_nop 1
	v_cndmask_b32_e32 v16, v11, v16, vcc
	v_cndmask_b32_e32 v10, v10, v19, vcc
	v_cndmask_b32_e32 v9, v9, v18, vcc
	v_cndmask_b32_e32 v17, 0, v17, vcc
	v_cmp_le_u32_e32 vcc, v31, v107
	s_nop 1
	v_cndmask_b32_e32 v18, 0, v9, vcc
	v_cmp_le_u32_e32 vcc, v30, v107
	s_nop 1
	v_cndmask_b32_e32 v19, 0, v10, vcc

.LBB0_222:
	s_or_b64 exec, exec, s[4:5]
	v_cmp_lt_u32_e32 vcc, 1, v108
	v_mov_b32_e32 v9, 0
	v_mov_b32_e32 v10, 0
	v_mov_b32_e32 v11, 0
	s_and_saveexec_b64 s[4:5], vcc
	s_cbranch_execz .LBB0_226
	v_add_u32_e32 v8, 0x1080, v29
	ds_read2_b32 v[200:201], v8 offset1:1
	v_add_u32_e32 v251, 0x5480, v29
	ds_read2_b32 v[202:203], v251 offset1:1
	v_add_u32_e32 v250, 0x1088, v29
	ds_read2_b32 v[204:205], v250 offset1:1
	v_add_u32_e32 v249, 0x5488, v29
	ds_read2_b32 v[220:221], v249 offset1:1
	v_add_u32_e32 v248, 0x1090, v29
	ds_read2_b32 v[222:223], v248 offset1:1
	v_add_u32_e32 v247, 0x5490, v29
	ds_read2_b32 v[224:225], v247 offset1:1
	v_add_u32_e32 v246, 0x1098, v29
	ds_read2_b32 v[226:227], v246 offset1:1
	v_add_u32_e32 v245, 0x5498, v29
	ds_read2_b32 v[228:229], v245 offset1:1
	v_cmp_eq_u32_e64 s[36:37], 2, v108
	s_waitcnt lgkmcnt(1)
	v_sub_f32_e32 v8, v26, v200
	v_sub_f32_e32 v9, v25, v201
	v_min_f32_e32 v8, 0x42a00000, v8
	v_min_f32_e32 v9, 0x42a00000, v9
	v_mul_f32_e32 v8, 0x3fb8aa3b, v8
	v_mul_f32_e32 v9, 0x3fb8aa3b, v9
	v_exp_f32_e32 v8, v8
	v_exp_f32_e32 v9, v9
	s_waitcnt lgkmcnt(0)
	v_pk_mul_f32 v[8:9], v[202:203], v[8:9]
	s_nop 0
	v_cvt_pk_bf16_f32 v8, v8, v9
	s_waitcnt lgkmcnt(0)
	v_sub_f32_e32 v9, v28, v204
	v_min_f32_e32 v9, 0x42a00000, v9
	v_mul_f32_e32 v9, 0x3fb8aa3b, v9
	v_exp_f32_e32 v10, v9
	v_sub_f32_e32 v9, v27, v205
	v_min_f32_e32 v9, 0x42a00000, v9
	v_mul_f32_e32 v9, 0x3fb8aa3b, v9
	v_exp_f32_e32 v11, v9
	s_waitcnt lgkmcnt(0)
	v_pk_mul_f32 v[10:11], v[220:221], v[10:11]
	s_nop 0
	v_cvt_pk_bf16_f32 v9, v10, v11
	s_waitcnt lgkmcnt(1)
	v_sub_f32_e32 v10, v21, v222
	v_sub_f32_e32 v11, v20, v223
	v_min_f32_e32 v10, 0x42a00000, v10
	v_min_f32_e32 v11, 0x42a00000, v11
	v_mul_f32_e32 v10, 0x3fb8aa3b, v10
	v_mul_f32_e32 v11, 0x3fb8aa3b, v11
	v_exp_f32_e32 v10, v10
	v_exp_f32_e32 v11, v11
	s_waitcnt lgkmcnt(0)
	v_pk_mul_f32 v[10:11], v[224:225], v[10:11]
	s_nop 0
	v_cvt_pk_bf16_f32 v10, v10, v11
	s_waitcnt lgkmcnt(0)
	v_sub_f32_e32 v11, v23, v226
	v_min_f32_e32 v11, 0x42a00000, v11
	v_mul_f32_e32 v11, 0x3fb8aa3b, v11
	v_exp_f32_e32 v12, v11
	v_sub_f32_e32 v11, v22, v227
	v_min_f32_e32 v11, 0x42a00000, v11
	v_mul_f32_e32 v11, 0x3fb8aa3b, v11
	v_exp_f32_e32 v13, v11
	s_waitcnt lgkmcnt(0)
	v_pk_mul_f32 v[12:13], v[228:229], v[12:13]
	s_nop 0
	v_cvt_pk_bf16_f32 v11, v12, v13
	s_nop 1
	v_mfma_f32_16x16x32_bf16 v[8:11], v[8:11], v[0:3], 0
	s_waitcnt lgkmcnt(0)
	v_mov_b32_e32 v32, v228
	v_mov_b32_e32 v33, v229
	s_and_saveexec_b64 s[2:3], s[36:37]
	s_cbranch_execz .LBB0_225
	v_cmp_gt_u32_e64 s[36:37], v24, v107
	s_nop 4
	v_cndmask_b32_e64 v12, v10, v10, s[36:37]
	v_cndmask_b32_e64 v13, v11, v11, s[36:37]
	v_cndmask_b32_e64 v14, v8, 0, s[36:37]
	v_cmp_lt_u32_e64 s[36:37], v24, v107
	s_nop 1
	v_cndmask_b32_e64 v8, v14, v8, s[36:37]
	v_cndmask_b32_e64 v11, v13, v11, s[36:37]
	v_cndmask_b32_e64 v10, v12, v10, s[36:37]
	v_cndmask_b32_e64 v9, 0, v9, s[36:37]
	v_cmp_le_u32_e64 s[36:37], v31, v107
	s_nop 1
	v_cndmask_b32_e64 v10, 0, v10, s[36:37]
	v_cmp_le_u32_e64 s[36:37], v30, v107
	s_nop 1
	v_cndmask_b32_e64 v11, 0, v11, s[36:37]

.LBB0_226:
	s_or_b64 exec, exec, s[4:5]
	v_cmp_eq_u32_e64 s[36:37], 3, v108
	v_mov_b32_e32 v12, 0
	v_mov_b32_e32 v13, 0
	v_mov_b32_e32 v14, 0
	v_mov_b32_e32 v32, 0
	s_and_saveexec_b64 s[4:5], s[36:37]
	s_cbranch_execz .LBB0_228
	v_add_u32_e32 v12, 0x18c0, v29
	v_add_u32_e32 v32, 0x18c8, v29
	v_add_u32_e32 v34, 0x5cc8, v29
	v_add_u32_e32 v14, 0x5cc0, v29
	ds_read2_b32 v[200:201], v12 offset1:1
	ds_read2_b32 v[202:203], v32 offset1:1
	ds_read2_b32 v[204:205], v34 offset1:1
	ds_read2_b32 v[220:221], v14 offset1:1
	v_add_u32_e32 v251, 0x18d0, v29
	ds_read2_b32 v[222:223], v251 offset1:1
	v_add_u32_e32 v250, 0x5cd0, v29
	ds_read2_b32 v[224:225], v250 offset1:1
	v_add_u32_e32 v249, 0x18d8, v29
	ds_read2_b32 v[226:227], v249 offset1:1
	v_add_u32_e32 v248, 0x5cd8, v29
	ds_read2_b32 v[228:229], v248 offset1:1
	v_cmp_lt_u32_e64 s[36:37], v24, v107
	s_waitcnt lgkmcnt(2)
	v_sub_f32_e32 v14, v28, v202
	v_min_f32_e32 v14, 0x42a00000, v14
	v_sub_f32_e32 v12, v26, v200
	v_sub_f32_e32 v13, v25, v201
	v_mul_f32_e32 v14, 0x3fb8aa3b, v14
	v_min_f32_e32 v12, 0x42a00000, v12
	v_min_f32_e32 v13, 0x42a00000, v13
	v_exp_f32_e32 v32, v14
	v_sub_f32_e32 v14, v27, v203
	v_mul_f32_e32 v12, 0x3fb8aa3b, v12
	v_mul_f32_e32 v13, 0x3fb8aa3b, v13
	v_min_f32_e32 v14, 0x42a00000, v14
	v_exp_f32_e32 v12, v12
	v_exp_f32_e32 v13, v13
	v_mul_f32_e32 v14, 0x3fb8aa3b, v14
	v_exp_f32_e32 v33, v14
	s_waitcnt lgkmcnt(0)
	v_pk_mul_f32 v[12:13], v[220:221], v[12:13]
	v_cvt_pk_bf16_f32 v26, v12, v13
	v_pk_mul_f32 v[12:13], v[204:205], v[32:33]
	v_cvt_pk_bf16_f32 v27, v12, v13
	s_waitcnt lgkmcnt(3)
	v_sub_f32_e32 v14, v21, v222
	v_min_f32_e32 v14, 0x42a00000, v14
	v_mul_f32_e32 v14, 0x3fb8aa3b, v14
	v_exp_f32_e32 v32, v14
	v_sub_f32_e32 v14, v20, v223
	v_min_f32_e32 v14, 0x42a00000, v14
	v_mul_f32_e32 v14, 0x3fb8aa3b, v14
	v_exp_f32_e32 v33, v14
	s_waitcnt lgkmcnt(1)
	v_sub_f32_e32 v14, v23, v226
	v_min_f32_e32 v14, 0x42a00000, v14
	v_mul_f32_e32 v14, 0x3fb8aa3b, v14
	v_exp_f32_e32 v20, v14
	v_sub_f32_e32 v14, v22, v227
	v_min_f32_e32 v14, 0x42a00000, v14
	v_mul_f32_e32 v14, 0x3fb8aa3b, v14
	v_exp_f32_e32 v21, v14
	v_pk_mul_f32 v[12:13], v[224:225], v[32:33]
	s_nop 0
	v_cvt_pk_bf16_f32 v28, v12, v13
	s_waitcnt lgkmcnt(0)
	v_pk_mul_f32 v[12:13], v[228:229], v[20:21]
	s_nop 0
	v_cvt_pk_bf16_f32 v29, v12, v13
	s_nop 1
	v_mfma_f32_16x16x32_bf16 v[0:3], v[26:29], v[0:3], 0
	s_nop 7
	v_cndmask_b32_e64 v13, 0, v1, s[36:37]
	v_cmp_le_u32_e64 s[36:37], v24, v107
	s_nop 1
	v_cndmask_b32_e64 v12, 0, v0, s[36:37]
	v_cmp_le_u32_e64 s[36:37], v31, v107
	s_nop 1
	v_cndmask_b32_e64 v14, 0, v2, s[36:37]
	v_cmp_le_u32_e64 s[36:37], v30, v107
	s_nop 1
	v_cndmask_b32_e64 v32, 0, v3, s[36:37]
	s_waitcnt lgkmcnt(0)
	v_mov_b32_e32 v34, v226
	v_mov_b32_e32 v35, v227
	v_mov_b32_e32 v36, v228
	v_mov_b32_e32 v37, v229

.LBB0_234:
	v_and_b32_e32 v70, 1, v210
	v_lshlrev_b32_e32 v70, 6, v70
	s_add_i32 s2, s20, s72
	s_cmpk_gt_i32 s2, 0x4ff
	s_cbranch_scc1 .Lwarm_done_h
	v_readfirstlane_b32 s3, v206
	s_nop 3
	s_lshr_b32 s3, s3, 6
	s_lshr_b32 vcc_lo, s3, 2
	s_and_b32 s3, s3, 3
	s_cmpk_lt_i32 s2, 0x300
	s_cselect_b32 s100, 1, 0
	s_movk_i32 s101, 0x300
	s_cselect_b32 s101, 0x100, s101
	s_sub_i32 s2, s2, s101
	s_lshl_b32 s2, s2, 1
	s_add_i32 s2, s2, vcc_lo
	s_sub_i32 vcc_hi, 3, s3
	s_cmp_eq_u32 vcc_lo, 0
	s_cselect_b32 vcc_hi, s3, vcc_hi
	s_lshr_b32 vcc_lo, s2, 7
	s_and_b32 s101, vcc_lo, 3
	s_lshr_b32 vcc_lo, vcc_lo, 2
	s_lshl_b32 vcc_lo, vcc_lo, 13
	s_and_b32 s2, s2, 0x7f
	s_lshl_b32 s2, s2, 6
	s_add_i32 s2, s2, vcc_lo
	s_lshl_b32 s3, s3, 4
	s_add_i32 s3, s3, s2
	s_lshl_b32 vcc_hi, vcc_hi, 4
	s_add_i32 vcc_hi, vcc_hi, s2
	s_lshl_b32 s2, s3, 6
	s_mul_i32 s3, s3, 0x1400
	s_mul_i32 vcc_hi, vcc_hi, 0x1400
	s_lshl_b32 vcc_lo, s101, 6
	s_cmp_eq_u32 s100, 1
	s_cbranch_scc0 .Lwarm_gla_h
	s_lshl_b32 vcc_lo, vcc_lo, 1
	s_add_u32 s100, s76, s3
	s_addc_u32 s101, s77, 0
	s_add_u32 s100, s100, vcc_lo
	s_addc_u32 s101, s101, 0
	global_load_dword v69, v70, s[100:101] offset:1536
	global_load_dword v69, v70, s[100:101] offset:2048
	s_add_u32 s100, s100, 0x1400
	s_addc_u32 s101, s101, 0
	global_load_dword v69, v70, s[100:101] offset:1536
	global_load_dword v69, v70, s[100:101] offset:2048
	s_add_u32 s100, s100, 0x1400
	s_addc_u32 s101, s101, 0
	global_load_dword v69, v70, s[100:101] offset:1536
	global_load_dword v69, v70, s[100:101] offset:2048
	s_add_u32 s100, s100, 0x1400
	s_addc_u32 s101, s101, 0
	global_load_dword v69, v70, s[100:101] offset:1536
	global_load_dword v69, v70, s[100:101] offset:2048
	s_add_u32 s100, s100, 0x1400
	s_addc_u32 s101, s101, 0
	global_load_dword v69, v70, s[100:101] offset:1536
	global_load_dword v69, v70, s[100:101] offset:2048
	s_add_u32 s100, s100, 0x1400
	s_addc_u32 s101, s101, 0
	global_load_dword v69, v70, s[100:101] offset:1536
	global_load_dword v69, v70, s[100:101] offset:2048
	s_add_u32 s100, s100, 0x1400
	s_addc_u32 s101, s101, 0
	global_load_dword v69, v70, s[100:101] offset:1536
	global_load_dword v69, v70, s[100:101] offset:2048
	s_add_u32 s100, s100, 0x1400
	s_addc_u32 s101, s101, 0
	global_load_dword v69, v70, s[100:101] offset:1536
	global_load_dword v69, v70, s[100:101] offset:2048
	s_add_u32 s100, s100, 0x1400
	s_addc_u32 s101, s101, 0
	global_load_dword v69, v70, s[100:101] offset:1536
	global_load_dword v69, v70, s[100:101] offset:2048
	s_add_u32 s100, s100, 0x1400
	s_addc_u32 s101, s101, 0
	global_load_dword v69, v70, s[100:101] offset:1536
	global_load_dword v69, v70, s[100:101] offset:2048
	s_add_u32 s100, s100, 0x1400
	s_addc_u32 s101, s101, 0
	global_load_dword v69, v70, s[100:101] offset:1536
	global_load_dword v69, v70, s[100:101] offset:2048
	s_add_u32 s100, s100, 0x1400
	s_addc_u32 s101, s101, 0
	global_load_dword v69, v70, s[100:101] offset:1536
	global_load_dword v69, v70, s[100:101] offset:2048
	s_add_u32 s100, s100, 0x1400
	s_addc_u32 s101, s101, 0
	global_load_dword v69, v70, s[100:101] offset:1536
	global_load_dword v69, v70, s[100:101] offset:2048
	s_add_u32 s100, s100, 0x1400
	s_addc_u32 s101, s101, 0
	global_load_dword v69, v70, s[100:101] offset:1536
	global_load_dword v69, v70, s[100:101] offset:2048
	s_add_u32 s100, s100, 0x1400
	s_addc_u32 s101, s101, 0
	global_load_dword v69, v70, s[100:101] offset:1536
	global_load_dword v69, v70, s[100:101] offset:2048
	s_add_u32 s100, s100, 0x1400
	s_addc_u32 s101, s101, 0
	global_load_dword v69, v70, s[100:101] offset:1536
	global_load_dword v69, v70, s[100:101] offset:2048
	s_add_u32 s100, s76, vcc_hi
	s_addc_u32 s101, s77, 0
	s_add_u32 s100, s100, vcc_lo
	s_addc_u32 s101, s101, 0
	global_load_dword v69, v70, s[100:101] offset:2560
	s_add_u32 s100, s100, 0x1400
	s_addc_u32 s101, s101, 0
	global_load_dword v69, v70, s[100:101] offset:2560
	s_add_u32 s100, s100, 0x1400
	s_addc_u32 s101, s101, 0
	global_load_dword v69, v70, s[100:101] offset:2560
	s_add_u32 s100, s100, 0x1400
	s_addc_u32 s101, s101, 0
	global_load_dword v69, v70, s[100:101] offset:2560
	s_add_u32 s100, s100, 0x1400
	s_addc_u32 s101, s101, 0
	global_load_dword v69, v70, s[100:101] offset:2560
	s_add_u32 s100, s100, 0x1400
	s_addc_u32 s101, s101, 0
	global_load_dword v69, v70, s[100:101] offset:2560
	s_add_u32 s100, s100, 0x1400
	s_addc_u32 s101, s101, 0
	global_load_dword v69, v70, s[100:101] offset:2560
	s_add_u32 s100, s100, 0x1400
	s_addc_u32 s101, s101, 0
	global_load_dword v69, v70, s[100:101] offset:2560
	s_add_u32 s100, s100, 0x1400
	s_addc_u32 s101, s101, 0
	global_load_dword v69, v70, s[100:101] offset:2560
	s_add_u32 s100, s100, 0x1400
	s_addc_u32 s101, s101, 0
	global_load_dword v69, v70, s[100:101] offset:2560
	s_add_u32 s100, s100, 0x1400
	s_addc_u32 s101, s101, 0
	global_load_dword v69, v70, s[100:101] offset:2560
	s_add_u32 s100, s100, 0x1400
	s_addc_u32 s101, s101, 0
	global_load_dword v69, v70, s[100:101] offset:2560
	s_add_u32 s100, s100, 0x1400
	s_addc_u32 s101, s101, 0
	global_load_dword v69, v70, s[100:101] offset:2560
	s_add_u32 s100, s100, 0x1400
	s_addc_u32 s101, s101, 0
	global_load_dword v69, v70, s[100:101] offset:2560
	s_add_u32 s100, s100, 0x1400
	s_addc_u32 s101, s101, 0
	global_load_dword v69, v70, s[100:101] offset:2560
	s_add_u32 s100, s100, 0x1400
	s_addc_u32 s101, s101, 0
	global_load_dword v69, v70, s[100:101] offset:2560
	s_branch .Lwarm_done_h
.Lwarm_gla_h:
	s_add_u32 s100, s76, s3
	s_addc_u32 s101, s77, 0
	s_add_u32 s100, s100, vcc_lo
	s_addc_u32 s101, s101, 0
	global_load_dword v69, v70, s[100:101] offset:3840
	s_add_u32 s100, s100, 0x1400
	s_addc_u32 s101, s101, 0
	global_load_dword v69, v70, s[100:101] offset:3840
	s_add_u32 s100, s100, 0x1400
	s_addc_u32 s101, s101, 0
	global_load_dword v69, v70, s[100:101] offset:3840
	s_add_u32 s100, s100, 0x1400
	s_addc_u32 s101, s101, 0
	global_load_dword v69, v70, s[100:101] offset:3840
	s_add_u32 s100, s100, 0x1400
	s_addc_u32 s101, s101, 0
	global_load_dword v69, v70, s[100:101] offset:3840
	s_add_u32 s100, s100, 0x1400
	s_addc_u32 s101, s101, 0
	global_load_dword v69, v70, s[100:101] offset:3840
	s_add_u32 s100, s100, 0x1400
	s_addc_u32 s101, s101, 0
	global_load_dword v69, v70, s[100:101] offset:3840
	s_add_u32 s100, s100, 0x1400
	s_addc_u32 s101, s101, 0
	global_load_dword v69, v70, s[100:101] offset:3840
	s_add_u32 s100, s100, 0x1400
	s_addc_u32 s101, s101, 0
	global_load_dword v69, v70, s[100:101] offset:3840
	s_add_u32 s100, s100, 0x1400
	s_addc_u32 s101, s101, 0
	global_load_dword v69, v70, s[100:101] offset:3840
	s_add_u32 s100, s100, 0x1400
	s_addc_u32 s101, s101, 0
	global_load_dword v69, v70, s[100:101] offset:3840
	s_add_u32 s100, s100, 0x1400
	s_addc_u32 s101, s101, 0
	global_load_dword v69, v70, s[100:101] offset:3840
	s_add_u32 s100, s100, 0x1400
	s_addc_u32 s101, s101, 0
	global_load_dword v69, v70, s[100:101] offset:3840
	s_add_u32 s100, s100, 0x1400
	s_addc_u32 s101, s101, 0
	global_load_dword v69, v70, s[100:101] offset:3840
	s_add_u32 s100, s100, 0x1400
	s_addc_u32 s101, s101, 0
	global_load_dword v69, v70, s[100:101] offset:3840
	s_add_u32 s100, s100, 0x1400
	s_addc_u32 s101, s101, 0
	global_load_dword v69, v70, s[100:101] offset:3840
	s_add_u32 s100, s76, vcc_hi
	s_addc_u32 s101, s77, 0
	s_add_u32 s100, s100, vcc_lo
	s_addc_u32 s101, s101, 0
	global_load_dword v69, v70, s[100:101] offset:3584
	s_add_u32 s100, s100, 0x1400
	s_addc_u32 s101, s101, 0
	global_load_dword v69, v70, s[100:101] offset:3584
	s_add_u32 s100, s100, 0x1400
	s_addc_u32 s101, s101, 0
	global_load_dword v69, v70, s[100:101] offset:3584
	s_add_u32 s100, s100, 0x1400
	s_addc_u32 s101, s101, 0
	global_load_dword v69, v70, s[100:101] offset:3584
	s_add_u32 s100, s100, 0x1400
	s_addc_u32 s101, s101, 0
	global_load_dword v69, v70, s[100:101] offset:3584
	s_add_u32 s100, s100, 0x1400
	s_addc_u32 s101, s101, 0
	global_load_dword v69, v70, s[100:101] offset:3584
	s_add_u32 s100, s100, 0x1400
	s_addc_u32 s101, s101, 0
	global_load_dword v69, v70, s[100:101] offset:3584
	s_add_u32 s100, s100, 0x1400
	s_addc_u32 s101, s101, 0
	global_load_dword v69, v70, s[100:101] offset:3584
	s_add_u32 s100, s100, 0x1400
	s_addc_u32 s101, s101, 0
	global_load_dword v69, v70, s[100:101] offset:3584
	s_add_u32 s100, s100, 0x1400
	s_addc_u32 s101, s101, 0
	global_load_dword v69, v70, s[100:101] offset:3584
	s_add_u32 s100, s100, 0x1400
	s_addc_u32 s101, s101, 0
	global_load_dword v69, v70, s[100:101] offset:3584
	s_add_u32 s100, s100, 0x1400
	s_addc_u32 s101, s101, 0
	global_load_dword v69, v70, s[100:101] offset:3584
	s_add_u32 s100, s100, 0x1400
	s_addc_u32 s101, s101, 0
	global_load_dword v69, v70, s[100:101] offset:3584
	s_add_u32 s100, s100, 0x1400
	s_addc_u32 s101, s101, 0
	global_load_dword v69, v70, s[100:101] offset:3584
	s_add_u32 s100, s100, 0x1400
	s_addc_u32 s101, s101, 0
	global_load_dword v69, v70, s[100:101] offset:3584
	s_add_u32 s100, s100, 0x1400
	s_addc_u32 s101, s101, 0
	global_load_dword v69, v70, s[100:101] offset:3584
	s_lshl_b32 vcc_lo, vcc_lo, 1
	s_addk_i32 vcc_lo, 0x800
	s_add_u32 s100, s76, s3
	s_addc_u32 s101, s77, 0
	s_add_u32 s100, s100, vcc_lo
	s_addc_u32 s101, s101, 0
	global_load_dword v69, v70, s[100:101] offset:2048
	s_add_u32 s100, s100, 0x1400
	s_addc_u32 s101, s101, 0
	global_load_dword v69, v70, s[100:101] offset:2048
	s_add_u32 s100, s100, 0x1400
	s_addc_u32 s101, s101, 0
	global_load_dword v69, v70, s[100:101] offset:2048
	s_add_u32 s100, s100, 0x1400
	s_addc_u32 s101, s101, 0
	global_load_dword v69, v70, s[100:101] offset:2048
	s_add_u32 s100, s100, 0x1400
	s_addc_u32 s101, s101, 0
	global_load_dword v69, v70, s[100:101] offset:2048
	s_add_u32 s100, s100, 0x1400
	s_addc_u32 s101, s101, 0
	global_load_dword v69, v70, s[100:101] offset:2048
	s_add_u32 s100, s100, 0x1400
	s_addc_u32 s101, s101, 0
	global_load_dword v69, v70, s[100:101] offset:2048
	s_add_u32 s100, s100, 0x1400
	s_addc_u32 s101, s101, 0
	global_load_dword v69, v70, s[100:101] offset:2048
	s_add_u32 s100, s100, 0x1400
	s_addc_u32 s101, s101, 0
	global_load_dword v69, v70, s[100:101] offset:2048
	s_add_u32 s100, s100, 0x1400
	s_addc_u32 s101, s101, 0
	global_load_dword v69, v70, s[100:101] offset:2048
	s_add_u32 s100, s100, 0x1400
	s_addc_u32 s101, s101, 0
	global_load_dword v69, v70, s[100:101] offset:2048
	s_add_u32 s100, s100, 0x1400
	s_addc_u32 s101, s101, 0
	global_load_dword v69, v70, s[100:101] offset:2048
	s_add_u32 s100, s100, 0x1400
	s_addc_u32 s101, s101, 0
	global_load_dword v69, v70, s[100:101] offset:2048
	s_add_u32 s100, s100, 0x1400
	s_addc_u32 s101, s101, 0
	global_load_dword v69, v70, s[100:101] offset:2048
	s_add_u32 s100, s100, 0x1400
	s_addc_u32 s101, s101, 0
	global_load_dword v69, v70, s[100:101] offset:2048
	s_add_u32 s100, s100, 0x1400
	s_addc_u32 s101, s101, 0
	global_load_dword v69, v70, s[100:101] offset:2048
	s_add_u32 s100, s68, s2
	s_addc_u32 s101, s69, 0
	s_add_u32 s100, s100, 0xdae0000
	s_addc_u32 s101, s101, 0
	global_load_dword v69, v70, s[100:101] offset:0
	global_load_dword v69, v70, s[100:101] offset:128
	global_load_dword v69, v70, s[100:101] offset:256
	global_load_dword v69, v70, s[100:101] offset:384
	global_load_dword v69, v70, s[100:101] offset:512
	global_load_dword v69, v70, s[100:101] offset:640
	global_load_dword v69, v70, s[100:101] offset:768
	global_load_dword v69, v70, s[100:101] offset:896
